# G2 group-carry scan rewritten by hand: a thread's 62 loads issued up front (one memory round trip instead of four), same pk_fma / cvt_pk arithmetic and order
# baseline (speedup 1.0000x reference)
.LBB0_1323:
	s_or_b64 exec, exec, s[6:7]
	v_lshl_or_b32 v6, s2, 9, v0
	s_waitcnt lgkmcnt(0)
	v_lshlrev_b32_e32 v2, 2, v6
	v_and_b32_e32 v8, 0xfffc, v2
	v_mov_b32_e32 v9, 0
	v_lshrrev_b32_e32 v7, 2, v6
	s_mov_b32 s7, 0
	v_lshl_add_u64 v[2:3], s[0:1], 0, v[8:9]
	v_and_b32_e32 v8, 0x1c0, v7
	s_and_b32 s10, s2, 0xffffffe0
	s_mov_b32 s11, s7
	v_lshl_add_u64 v[4:5], s[8:9], 0, v[8:9]
	v_and_b32_e32 v8, 32, v7
	v_lshlrev_b32_e32 v6, 3, v6
	v_lshl_add_u64 v[4:5], v[4:5], 0, v[8:9]
	v_and_b32_e32 v8, 24, v6
	s_lshl_b64 s[8:9], s[10:11], 16
	v_lshl_add_u64 v[6:7], v[4:5], 0, v[8:9]
	v_lshl_add_u64 v[4:5], v[2:3], 0, s[8:9]
	s_lshl_b64 s[8:9], s[10:11], 9
	v_lshl_add_u64 v[10:11], v[6:7], 0, s[8:9]
	s_or_b32 s8, s10, 1
	s_mov_b32 s9, s7
	s_lshl_b64 s[16:17], s[8:9], 16
	v_lshl_add_u64 v[12:13], v[2:3], 0, s[16:17]
	s_lshl_b64 s[8:9], s[8:9], 9
	s_barrier
	v_mov_b32_e32 v38, 0
	v_mov_b32_e32 v39, 0
	s_or_b32 s8, s10, 0
	s_mov_b32 s9, s7
	s_lshl_b64 s[16:17], s[8:9], 16
	s_lshl_b64 s[8:9], s[8:9], 9
	v_lshl_add_u64 v[34:35], v[2:3], 0, s[16:17]
	global_load_dword v40, v[34:35], off
	v_lshl_add_u64 v[34:35], v[6:7], 0, s[8:9]
	global_load_dwordx2 v[72:73], v[34:35], off
	s_or_b32 s8, s10, 1
	s_mov_b32 s9, s7
	s_lshl_b64 s[16:17], s[8:9], 16
	s_lshl_b64 s[8:9], s[8:9], 9
	v_lshl_add_u64 v[34:35], v[2:3], 0, s[16:17]
	global_load_dword v41, v[34:35], off
	v_lshl_add_u64 v[34:35], v[6:7], 0, s[8:9]
	global_load_dwordx2 v[74:75], v[34:35], off
	s_or_b32 s8, s10, 2
	s_mov_b32 s9, s7
	s_lshl_b64 s[16:17], s[8:9], 16
	s_lshl_b64 s[8:9], s[8:9], 9
	v_lshl_add_u64 v[34:35], v[2:3], 0, s[16:17]
	global_load_dword v42, v[34:35], off
	v_lshl_add_u64 v[34:35], v[6:7], 0, s[8:9]
	global_load_dwordx2 v[76:77], v[34:35], off
	s_or_b32 s8, s10, 3
	s_mov_b32 s9, s7
	s_lshl_b64 s[16:17], s[8:9], 16
	s_lshl_b64 s[8:9], s[8:9], 9
	v_lshl_add_u64 v[34:35], v[2:3], 0, s[16:17]
	global_load_dword v43, v[34:35], off
	v_lshl_add_u64 v[34:35], v[6:7], 0, s[8:9]
	global_load_dwordx2 v[78:79], v[34:35], off
	s_or_b32 s8, s10, 4
	s_mov_b32 s9, s7
	s_lshl_b64 s[16:17], s[8:9], 16
	s_lshl_b64 s[8:9], s[8:9], 9
	v_lshl_add_u64 v[34:35], v[2:3], 0, s[16:17]
	global_load_dword v44, v[34:35], off
	v_lshl_add_u64 v[34:35], v[6:7], 0, s[8:9]
	global_load_dwordx2 v[80:81], v[34:35], off
	s_or_b32 s8, s10, 5
	s_mov_b32 s9, s7
	s_lshl_b64 s[16:17], s[8:9], 16
	s_lshl_b64 s[8:9], s[8:9], 9
	v_lshl_add_u64 v[34:35], v[2:3], 0, s[16:17]
	global_load_dword v45, v[34:35], off
	v_lshl_add_u64 v[34:35], v[6:7], 0, s[8:9]
	global_load_dwordx2 v[82:83], v[34:35], off
	s_or_b32 s8, s10, 6
	s_mov_b32 s9, s7
	s_lshl_b64 s[16:17], s[8:9], 16
	s_lshl_b64 s[8:9], s[8:9], 9
	v_lshl_add_u64 v[34:35], v[2:3], 0, s[16:17]
	global_load_dword v46, v[34:35], off
	v_lshl_add_u64 v[34:35], v[6:7], 0, s[8:9]
	global_load_dwordx2 v[84:85], v[34:35], off
	s_or_b32 s8, s10, 7
	s_mov_b32 s9, s7
	s_lshl_b64 s[16:17], s[8:9], 16
	s_lshl_b64 s[8:9], s[8:9], 9
	v_lshl_add_u64 v[34:35], v[2:3], 0, s[16:17]
	global_load_dword v47, v[34:35], off
	v_lshl_add_u64 v[34:35], v[6:7], 0, s[8:9]
	global_load_dwordx2 v[86:87], v[34:35], off
	s_or_b32 s8, s10, 8
	s_mov_b32 s9, s7
	s_lshl_b64 s[16:17], s[8:9], 16
	s_lshl_b64 s[8:9], s[8:9], 9
	v_lshl_add_u64 v[34:35], v[2:3], 0, s[16:17]
	global_load_dword v48, v[34:35], off
	v_lshl_add_u64 v[34:35], v[6:7], 0, s[8:9]
	global_load_dwordx2 v[88:89], v[34:35], off
	s_or_b32 s8, s10, 9
	s_mov_b32 s9, s7
	s_lshl_b64 s[16:17], s[8:9], 16
	s_lshl_b64 s[8:9], s[8:9], 9
	v_lshl_add_u64 v[34:35], v[2:3], 0, s[16:17]
	global_load_dword v49, v[34:35], off
	v_lshl_add_u64 v[34:35], v[6:7], 0, s[8:9]
	global_load_dwordx2 v[90:91], v[34:35], off
	s_or_b32 s8, s10, 10
	s_mov_b32 s9, s7
	s_lshl_b64 s[16:17], s[8:9], 16
	s_lshl_b64 s[8:9], s[8:9], 9
	v_lshl_add_u64 v[34:35], v[2:3], 0, s[16:17]
	global_load_dword v50, v[34:35], off
	v_lshl_add_u64 v[34:35], v[6:7], 0, s[8:9]
	global_load_dwordx2 v[92:93], v[34:35], off
	s_or_b32 s8, s10, 11
	s_mov_b32 s9, s7
	s_lshl_b64 s[16:17], s[8:9], 16
	s_lshl_b64 s[8:9], s[8:9], 9
	v_lshl_add_u64 v[34:35], v[2:3], 0, s[16:17]
	global_load_dword v51, v[34:35], off
	v_lshl_add_u64 v[34:35], v[6:7], 0, s[8:9]
	global_load_dwordx2 v[94:95], v[34:35], off
	s_or_b32 s8, s10, 12
	s_mov_b32 s9, s7
	s_lshl_b64 s[16:17], s[8:9], 16
	s_lshl_b64 s[8:9], s[8:9], 9
	v_lshl_add_u64 v[34:35], v[2:3], 0, s[16:17]
	global_load_dword v52, v[34:35], off
	v_lshl_add_u64 v[34:35], v[6:7], 0, s[8:9]
	global_load_dwordx2 v[96:97], v[34:35], off
	s_or_b32 s8, s10, 13
	s_mov_b32 s9, s7
	s_lshl_b64 s[16:17], s[8:9], 16
	s_lshl_b64 s[8:9], s[8:9], 9
	v_lshl_add_u64 v[34:35], v[2:3], 0, s[16:17]
	global_load_dword v53, v[34:35], off
	v_lshl_add_u64 v[34:35], v[6:7], 0, s[8:9]
	global_load_dwordx2 v[98:99], v[34:35], off
	s_or_b32 s8, s10, 14
	s_mov_b32 s9, s7
	s_lshl_b64 s[16:17], s[8:9], 16
	s_lshl_b64 s[8:9], s[8:9], 9
	v_lshl_add_u64 v[34:35], v[2:3], 0, s[16:17]
	global_load_dword v54, v[34:35], off
	v_lshl_add_u64 v[34:35], v[6:7], 0, s[8:9]
	global_load_dwordx2 v[100:101], v[34:35], off
	s_or_b32 s8, s10, 15
	s_mov_b32 s9, s7
	s_lshl_b64 s[16:17], s[8:9], 16
	s_lshl_b64 s[8:9], s[8:9], 9
	v_lshl_add_u64 v[34:35], v[2:3], 0, s[16:17]
	global_load_dword v55, v[34:35], off
	v_lshl_add_u64 v[34:35], v[6:7], 0, s[8:9]
	global_load_dwordx2 v[102:103], v[34:35], off
	s_or_b32 s8, s10, 16
	s_mov_b32 s9, s7
	s_lshl_b64 s[16:17], s[8:9], 16
	s_lshl_b64 s[8:9], s[8:9], 9
	v_lshl_add_u64 v[34:35], v[2:3], 0, s[16:17]
	global_load_dword v56, v[34:35], off
	v_lshl_add_u64 v[34:35], v[6:7], 0, s[8:9]
	global_load_dwordx2 v[104:105], v[34:35], off
	s_or_b32 s8, s10, 17
	s_mov_b32 s9, s7
	s_lshl_b64 s[16:17], s[8:9], 16
	s_lshl_b64 s[8:9], s[8:9], 9
	v_lshl_add_u64 v[34:35], v[2:3], 0, s[16:17]
	global_load_dword v57, v[34:35], off
	v_lshl_add_u64 v[34:35], v[6:7], 0, s[8:9]
	global_load_dwordx2 v[106:107], v[34:35], off
	s_or_b32 s8, s10, 18
	s_mov_b32 s9, s7
	s_lshl_b64 s[16:17], s[8:9], 16
	s_lshl_b64 s[8:9], s[8:9], 9
	v_lshl_add_u64 v[34:35], v[2:3], 0, s[16:17]
	global_load_dword v58, v[34:35], off
	v_lshl_add_u64 v[34:35], v[6:7], 0, s[8:9]
	global_load_dwordx2 v[108:109], v[34:35], off
	s_or_b32 s8, s10, 19
	s_mov_b32 s9, s7
	s_lshl_b64 s[16:17], s[8:9], 16
	s_lshl_b64 s[8:9], s[8:9], 9
	v_lshl_add_u64 v[34:35], v[2:3], 0, s[16:17]
	global_load_dword v59, v[34:35], off
	v_lshl_add_u64 v[34:35], v[6:7], 0, s[8:9]
	global_load_dwordx2 v[110:111], v[34:35], off
	s_or_b32 s8, s10, 20
	s_mov_b32 s9, s7
	s_lshl_b64 s[16:17], s[8:9], 16
	s_lshl_b64 s[8:9], s[8:9], 9
	v_lshl_add_u64 v[34:35], v[2:3], 0, s[16:17]
	global_load_dword v60, v[34:35], off
	v_lshl_add_u64 v[34:35], v[6:7], 0, s[8:9]
	global_load_dwordx2 v[112:113], v[34:35], off
	s_or_b32 s8, s10, 21
	s_mov_b32 s9, s7
	s_lshl_b64 s[16:17], s[8:9], 16
	s_lshl_b64 s[8:9], s[8:9], 9
	v_lshl_add_u64 v[34:35], v[2:3], 0, s[16:17]
	global_load_dword v61, v[34:35], off
	v_lshl_add_u64 v[34:35], v[6:7], 0, s[8:9]
	global_load_dwordx2 v[114:115], v[34:35], off
	s_or_b32 s8, s10, 22
	s_mov_b32 s9, s7
	s_lshl_b64 s[16:17], s[8:9], 16
	s_lshl_b64 s[8:9], s[8:9], 9
	v_lshl_add_u64 v[34:35], v[2:3], 0, s[16:17]
	global_load_dword v62, v[34:35], off
	v_lshl_add_u64 v[34:35], v[6:7], 0, s[8:9]
	global_load_dwordx2 v[116:117], v[34:35], off
	s_or_b32 s8, s10, 23
	s_mov_b32 s9, s7
	s_lshl_b64 s[16:17], s[8:9], 16
	s_lshl_b64 s[8:9], s[8:9], 9
	v_lshl_add_u64 v[34:35], v[2:3], 0, s[16:17]
	global_load_dword v63, v[34:35], off
	v_lshl_add_u64 v[34:35], v[6:7], 0, s[8:9]
	global_load_dwordx2 v[118:119], v[34:35], off
	s_or_b32 s8, s10, 24
	s_mov_b32 s9, s7
	s_lshl_b64 s[16:17], s[8:9], 16
	s_lshl_b64 s[8:9], s[8:9], 9
	v_lshl_add_u64 v[34:35], v[2:3], 0, s[16:17]
	global_load_dword v64, v[34:35], off
	v_lshl_add_u64 v[34:35], v[6:7], 0, s[8:9]
	global_load_dwordx2 v[120:121], v[34:35], off
	s_or_b32 s8, s10, 25
	s_mov_b32 s9, s7
	s_lshl_b64 s[16:17], s[8:9], 16
	s_lshl_b64 s[8:9], s[8:9], 9
	v_lshl_add_u64 v[34:35], v[2:3], 0, s[16:17]
	global_load_dword v65, v[34:35], off
	v_lshl_add_u64 v[34:35], v[6:7], 0, s[8:9]
	global_load_dwordx2 v[122:123], v[34:35], off
	s_or_b32 s8, s10, 26
	s_mov_b32 s9, s7
	s_lshl_b64 s[16:17], s[8:9], 16
	s_lshl_b64 s[8:9], s[8:9], 9
	v_lshl_add_u64 v[34:35], v[2:3], 0, s[16:17]
	global_load_dword v66, v[34:35], off
	v_lshl_add_u64 v[34:35], v[6:7], 0, s[8:9]
	global_load_dwordx2 v[124:125], v[34:35], off
	s_or_b32 s8, s10, 27
	s_mov_b32 s9, s7
	s_lshl_b64 s[16:17], s[8:9], 16
	s_lshl_b64 s[8:9], s[8:9], 9
	v_lshl_add_u64 v[34:35], v[2:3], 0, s[16:17]
	global_load_dword v67, v[34:35], off
	v_lshl_add_u64 v[34:35], v[6:7], 0, s[8:9]
	global_load_dwordx2 v[126:127], v[34:35], off
	s_or_b32 s8, s10, 28
	s_mov_b32 s9, s7
	s_lshl_b64 s[16:17], s[8:9], 16
	s_lshl_b64 s[8:9], s[8:9], 9
	v_lshl_add_u64 v[34:35], v[2:3], 0, s[16:17]
	global_load_dword v68, v[34:35], off
	v_lshl_add_u64 v[34:35], v[6:7], 0, s[8:9]
	global_load_dwordx2 v[128:129], v[34:35], off
	s_or_b32 s8, s10, 29
	s_mov_b32 s9, s7
	s_lshl_b64 s[16:17], s[8:9], 16
	s_lshl_b64 s[8:9], s[8:9], 9
	v_lshl_add_u64 v[34:35], v[2:3], 0, s[16:17]
	global_load_dword v69, v[34:35], off
	v_lshl_add_u64 v[34:35], v[6:7], 0, s[8:9]
	global_load_dwordx2 v[130:131], v[34:35], off
	s_or_b32 s8, s10, 30
	s_mov_b32 s9, s7
	s_lshl_b64 s[16:17], s[8:9], 16
	s_lshl_b64 s[8:9], s[8:9], 9
	v_lshl_add_u64 v[34:35], v[2:3], 0, s[16:17]
	global_load_dword v70, v[34:35], off
	v_lshl_add_u64 v[34:35], v[6:7], 0, s[8:9]
	global_load_dwordx2 v[132:133], v[34:35], off
	s_waitcnt vmcnt(60)
	v_lshlrev_b32_e32 v36, 16, v40
	v_and_b32_e32 v37, 0xffff0000, v40
	v_cvt_pk_bf16_f32 v40, v38, v39
	v_pk_fma_f32 v[38:39], v[72:73], v[38:39], v[36:37]
	s_waitcnt vmcnt(58)
	v_lshlrev_b32_e32 v36, 16, v41
	v_and_b32_e32 v37, 0xffff0000, v41
	v_cvt_pk_bf16_f32 v41, v38, v39
	v_pk_fma_f32 v[38:39], v[74:75], v[38:39], v[36:37]
	s_waitcnt vmcnt(56)
	v_lshlrev_b32_e32 v36, 16, v42
	v_and_b32_e32 v37, 0xffff0000, v42
	v_cvt_pk_bf16_f32 v42, v38, v39
	v_pk_fma_f32 v[38:39], v[76:77], v[38:39], v[36:37]
	s_waitcnt vmcnt(54)
	v_lshlrev_b32_e32 v36, 16, v43
	v_and_b32_e32 v37, 0xffff0000, v43
	v_cvt_pk_bf16_f32 v43, v38, v39
	v_pk_fma_f32 v[38:39], v[78:79], v[38:39], v[36:37]
	s_waitcnt vmcnt(52)
	v_lshlrev_b32_e32 v36, 16, v44
	v_and_b32_e32 v37, 0xffff0000, v44
	v_cvt_pk_bf16_f32 v44, v38, v39
	v_pk_fma_f32 v[38:39], v[80:81], v[38:39], v[36:37]
	s_waitcnt vmcnt(50)
	v_lshlrev_b32_e32 v36, 16, v45
	v_and_b32_e32 v37, 0xffff0000, v45
	v_cvt_pk_bf16_f32 v45, v38, v39
	v_pk_fma_f32 v[38:39], v[82:83], v[38:39], v[36:37]
	s_waitcnt vmcnt(48)
	v_lshlrev_b32_e32 v36, 16, v46
	v_and_b32_e32 v37, 0xffff0000, v46
	v_cvt_pk_bf16_f32 v46, v38, v39
	v_pk_fma_f32 v[38:39], v[84:85], v[38:39], v[36:37]
	s_waitcnt vmcnt(46)
	v_lshlrev_b32_e32 v36, 16, v47
	v_and_b32_e32 v37, 0xffff0000, v47
	v_cvt_pk_bf16_f32 v47, v38, v39
	v_pk_fma_f32 v[38:39], v[86:87], v[38:39], v[36:37]
	s_waitcnt vmcnt(44)
	v_lshlrev_b32_e32 v36, 16, v48
	v_and_b32_e32 v37, 0xffff0000, v48
	v_cvt_pk_bf16_f32 v48, v38, v39
	v_pk_fma_f32 v[38:39], v[88:89], v[38:39], v[36:37]
	s_waitcnt vmcnt(42)
	v_lshlrev_b32_e32 v36, 16, v49
	v_and_b32_e32 v37, 0xffff0000, v49
	v_cvt_pk_bf16_f32 v49, v38, v39
	v_pk_fma_f32 v[38:39], v[90:91], v[38:39], v[36:37]
	s_waitcnt vmcnt(40)
	v_lshlrev_b32_e32 v36, 16, v50
	v_and_b32_e32 v37, 0xffff0000, v50
	v_cvt_pk_bf16_f32 v50, v38, v39
	v_pk_fma_f32 v[38:39], v[92:93], v[38:39], v[36:37]
	s_waitcnt vmcnt(38)
	v_lshlrev_b32_e32 v36, 16, v51
	v_and_b32_e32 v37, 0xffff0000, v51
	v_cvt_pk_bf16_f32 v51, v38, v39
	v_pk_fma_f32 v[38:39], v[94:95], v[38:39], v[36:37]
	s_waitcnt vmcnt(36)
	v_lshlrev_b32_e32 v36, 16, v52
	v_and_b32_e32 v37, 0xffff0000, v52
	v_cvt_pk_bf16_f32 v52, v38, v39
	v_pk_fma_f32 v[38:39], v[96:97], v[38:39], v[36:37]
	s_waitcnt vmcnt(34)
	v_lshlrev_b32_e32 v36, 16, v53
	v_and_b32_e32 v37, 0xffff0000, v53
	v_cvt_pk_bf16_f32 v53, v38, v39
	v_pk_fma_f32 v[38:39], v[98:99], v[38:39], v[36:37]
	s_waitcnt vmcnt(32)
	v_lshlrev_b32_e32 v36, 16, v54
	v_and_b32_e32 v37, 0xffff0000, v54
	v_cvt_pk_bf16_f32 v54, v38, v39
	v_pk_fma_f32 v[38:39], v[100:101], v[38:39], v[36:37]
	s_waitcnt vmcnt(30)
	v_lshlrev_b32_e32 v36, 16, v55
	v_and_b32_e32 v37, 0xffff0000, v55
	v_cvt_pk_bf16_f32 v55, v38, v39
	v_pk_fma_f32 v[38:39], v[102:103], v[38:39], v[36:37]
	s_waitcnt vmcnt(28)
	v_lshlrev_b32_e32 v36, 16, v56
	v_and_b32_e32 v37, 0xffff0000, v56
	v_cvt_pk_bf16_f32 v56, v38, v39
	v_pk_fma_f32 v[38:39], v[104:105], v[38:39], v[36:37]
	s_waitcnt vmcnt(26)
	v_lshlrev_b32_e32 v36, 16, v57
	v_and_b32_e32 v37, 0xffff0000, v57
	v_cvt_pk_bf16_f32 v57, v38, v39
	v_pk_fma_f32 v[38:39], v[106:107], v[38:39], v[36:37]
	s_waitcnt vmcnt(24)
	v_lshlrev_b32_e32 v36, 16, v58
	v_and_b32_e32 v37, 0xffff0000, v58
	v_cvt_pk_bf16_f32 v58, v38, v39
	v_pk_fma_f32 v[38:39], v[108:109], v[38:39], v[36:37]
	s_waitcnt vmcnt(22)
	v_lshlrev_b32_e32 v36, 16, v59
	v_and_b32_e32 v37, 0xffff0000, v59
	v_cvt_pk_bf16_f32 v59, v38, v39
	v_pk_fma_f32 v[38:39], v[110:111], v[38:39], v[36:37]
	s_waitcnt vmcnt(20)
	v_lshlrev_b32_e32 v36, 16, v60
	v_and_b32_e32 v37, 0xffff0000, v60
	v_cvt_pk_bf16_f32 v60, v38, v39
	v_pk_fma_f32 v[38:39], v[112:113], v[38:39], v[36:37]
	s_waitcnt vmcnt(18)
	v_lshlrev_b32_e32 v36, 16, v61
	v_and_b32_e32 v37, 0xffff0000, v61
	v_cvt_pk_bf16_f32 v61, v38, v39
	v_pk_fma_f32 v[38:39], v[114:115], v[38:39], v[36:37]
	s_waitcnt vmcnt(16)
	v_lshlrev_b32_e32 v36, 16, v62
	v_and_b32_e32 v37, 0xffff0000, v62
	v_cvt_pk_bf16_f32 v62, v38, v39
	v_pk_fma_f32 v[38:39], v[116:117], v[38:39], v[36:37]
	s_waitcnt vmcnt(14)
	v_lshlrev_b32_e32 v36, 16, v63
	v_and_b32_e32 v37, 0xffff0000, v63
	v_cvt_pk_bf16_f32 v63, v38, v39
	v_pk_fma_f32 v[38:39], v[118:119], v[38:39], v[36:37]
	s_waitcnt vmcnt(12)
	v_lshlrev_b32_e32 v36, 16, v64
	v_and_b32_e32 v37, 0xffff0000, v64
	v_cvt_pk_bf16_f32 v64, v38, v39
	v_pk_fma_f32 v[38:39], v[120:121], v[38:39], v[36:37]
	s_waitcnt vmcnt(10)
	v_lshlrev_b32_e32 v36, 16, v65
	v_and_b32_e32 v37, 0xffff0000, v65
	v_cvt_pk_bf16_f32 v65, v38, v39
	v_pk_fma_f32 v[38:39], v[122:123], v[38:39], v[36:37]
	s_waitcnt vmcnt(8)
	v_lshlrev_b32_e32 v36, 16, v66
	v_and_b32_e32 v37, 0xffff0000, v66
	v_cvt_pk_bf16_f32 v66, v38, v39
	v_pk_fma_f32 v[38:39], v[124:125], v[38:39], v[36:37]
	s_waitcnt vmcnt(6)
	v_lshlrev_b32_e32 v36, 16, v67
	v_and_b32_e32 v37, 0xffff0000, v67
	v_cvt_pk_bf16_f32 v67, v38, v39
	v_pk_fma_f32 v[38:39], v[126:127], v[38:39], v[36:37]
	s_waitcnt vmcnt(4)
	v_lshlrev_b32_e32 v36, 16, v68
	v_and_b32_e32 v37, 0xffff0000, v68
	v_cvt_pk_bf16_f32 v68, v38, v39
	v_pk_fma_f32 v[38:39], v[128:129], v[38:39], v[36:37]
	s_waitcnt vmcnt(2)
	v_lshlrev_b32_e32 v36, 16, v69
	v_and_b32_e32 v37, 0xffff0000, v69
	v_cvt_pk_bf16_f32 v69, v38, v39
	v_pk_fma_f32 v[38:39], v[130:131], v[38:39], v[36:37]
	s_waitcnt vmcnt(0)
	v_lshlrev_b32_e32 v36, 16, v70
	v_and_b32_e32 v37, 0xffff0000, v70
	v_cvt_pk_bf16_f32 v70, v38, v39
	v_pk_fma_f32 v[38:39], v[132:133], v[38:39], v[36:37]
	v_cvt_pk_bf16_f32 v71, v38, v39
	s_or_b32 s8, s10, 0
	s_mov_b32 s9, s7
	s_lshl_b64 s[16:17], s[8:9], 16
	v_lshl_add_u64 v[34:35], v[2:3], 0, s[16:17]
	global_store_dword v[34:35], v40, off
	s_or_b32 s8, s10, 1
	s_mov_b32 s9, s7
	s_lshl_b64 s[16:17], s[8:9], 16
	v_lshl_add_u64 v[34:35], v[2:3], 0, s[16:17]
	global_store_dword v[34:35], v41, off
	s_or_b32 s8, s10, 2
	s_mov_b32 s9, s7
	s_lshl_b64 s[16:17], s[8:9], 16
	v_lshl_add_u64 v[34:35], v[2:3], 0, s[16:17]
	global_store_dword v[34:35], v42, off
	s_or_b32 s8, s10, 3
	s_mov_b32 s9, s7
	s_lshl_b64 s[16:17], s[8:9], 16
	v_lshl_add_u64 v[34:35], v[2:3], 0, s[16:17]
	global_store_dword v[34:35], v43, off
	s_or_b32 s8, s10, 4
	s_mov_b32 s9, s7
	s_lshl_b64 s[16:17], s[8:9], 16
	v_lshl_add_u64 v[34:35], v[2:3], 0, s[16:17]
	global_store_dword v[34:35], v44, off
	s_or_b32 s8, s10, 5
	s_mov_b32 s9, s7
	s_lshl_b64 s[16:17], s[8:9], 16
	v_lshl_add_u64 v[34:35], v[2:3], 0, s[16:17]
	global_store_dword v[34:35], v45, off
	s_or_b32 s8, s10, 6
	s_mov_b32 s9, s7
	s_lshl_b64 s[16:17], s[8:9], 16
	v_lshl_add_u64 v[34:35], v[2:3], 0, s[16:17]
	global_store_dword v[34:35], v46, off
	s_or_b32 s8, s10, 7
	s_mov_b32 s9, s7
	s_lshl_b64 s[16:17], s[8:9], 16
	v_lshl_add_u64 v[34:35], v[2:3], 0, s[16:17]
	global_store_dword v[34:35], v47, off
	s_or_b32 s8, s10, 8
	s_mov_b32 s9, s7
	s_lshl_b64 s[16:17], s[8:9], 16
	v_lshl_add_u64 v[34:35], v[2:3], 0, s[16:17]
	global_store_dword v[34:35], v48, off
	s_or_b32 s8, s10, 9
	s_mov_b32 s9, s7
	s_lshl_b64 s[16:17], s[8:9], 16
	v_lshl_add_u64 v[34:35], v[2:3], 0, s[16:17]
	global_store_dword v[34:35], v49, off
	s_or_b32 s8, s10, 10
	s_mov_b32 s9, s7
	s_lshl_b64 s[16:17], s[8:9], 16
	v_lshl_add_u64 v[34:35], v[2:3], 0, s[16:17]
	global_store_dword v[34:35], v50, off
	s_or_b32 s8, s10, 11
	s_mov_b32 s9, s7
	s_lshl_b64 s[16:17], s[8:9], 16
	v_lshl_add_u64 v[34:35], v[2:3], 0, s[16:17]
	global_store_dword v[34:35], v51, off
	s_or_b32 s8, s10, 12
	s_mov_b32 s9, s7
	s_lshl_b64 s[16:17], s[8:9], 16
	v_lshl_add_u64 v[34:35], v[2:3], 0, s[16:17]
	global_store_dword v[34:35], v52, off
	s_or_b32 s8, s10, 13
	s_mov_b32 s9, s7
	s_lshl_b64 s[16:17], s[8:9], 16
	v_lshl_add_u64 v[34:35], v[2:3], 0, s[16:17]
	global_store_dword v[34:35], v53, off
	s_or_b32 s8, s10, 14
	s_mov_b32 s9, s7
	s_lshl_b64 s[16:17], s[8:9], 16
	v_lshl_add_u64 v[34:35], v[2:3], 0, s[16:17]
	global_store_dword v[34:35], v54, off
	s_or_b32 s8, s10, 15
	s_mov_b32 s9, s7
	s_lshl_b64 s[16:17], s[8:9], 16
	v_lshl_add_u64 v[34:35], v[2:3], 0, s[16:17]
	global_store_dword v[34:35], v55, off
	s_or_b32 s8, s10, 16
	s_mov_b32 s9, s7
	s_lshl_b64 s[16:17], s[8:9], 16
	v_lshl_add_u64 v[34:35], v[2:3], 0, s[16:17]
	global_store_dword v[34:35], v56, off
	s_or_b32 s8, s10, 17
	s_mov_b32 s9, s7
	s_lshl_b64 s[16:17], s[8:9], 16
	v_lshl_add_u64 v[34:35], v[2:3], 0, s[16:17]
	global_store_dword v[34:35], v57, off
	s_or_b32 s8, s10, 18
	s_mov_b32 s9, s7
	s_lshl_b64 s[16:17], s[8:9], 16
	v_lshl_add_u64 v[34:35], v[2:3], 0, s[16:17]
	global_store_dword v[34:35], v58, off
	s_or_b32 s8, s10, 19
	s_mov_b32 s9, s7
	s_lshl_b64 s[16:17], s[8:9], 16
	v_lshl_add_u64 v[34:35], v[2:3], 0, s[16:17]
	global_store_dword v[34:35], v59, off
	s_or_b32 s8, s10, 20
	s_mov_b32 s9, s7
	s_lshl_b64 s[16:17], s[8:9], 16
	v_lshl_add_u64 v[34:35], v[2:3], 0, s[16:17]
	global_store_dword v[34:35], v60, off
	s_or_b32 s8, s10, 21
	s_mov_b32 s9, s7
	s_lshl_b64 s[16:17], s[8:9], 16
	v_lshl_add_u64 v[34:35], v[2:3], 0, s[16:17]
	global_store_dword v[34:35], v61, off
	s_or_b32 s8, s10, 22
	s_mov_b32 s9, s7
	s_lshl_b64 s[16:17], s[8:9], 16
	v_lshl_add_u64 v[34:35], v[2:3], 0, s[16:17]
	global_store_dword v[34:35], v62, off
	s_or_b32 s8, s10, 23
	s_mov_b32 s9, s7
	s_lshl_b64 s[16:17], s[8:9], 16
	v_lshl_add_u64 v[34:35], v[2:3], 0, s[16:17]
	global_store_dword v[34:35], v63, off
	s_or_b32 s8, s10, 24
	s_mov_b32 s9, s7
	s_lshl_b64 s[16:17], s[8:9], 16
	v_lshl_add_u64 v[34:35], v[2:3], 0, s[16:17]
	global_store_dword v[34:35], v64, off
	s_or_b32 s8, s10, 25
	s_mov_b32 s9, s7
	s_lshl_b64 s[16:17], s[8:9], 16
	v_lshl_add_u64 v[34:35], v[2:3], 0, s[16:17]
	global_store_dword v[34:35], v65, off
	s_or_b32 s8, s10, 26
	s_mov_b32 s9, s7
	s_lshl_b64 s[16:17], s[8:9], 16
	v_lshl_add_u64 v[34:35], v[2:3], 0, s[16:17]
	global_store_dword v[34:35], v66, off
	s_or_b32 s8, s10, 27
	s_mov_b32 s9, s7
	s_lshl_b64 s[16:17], s[8:9], 16
	v_lshl_add_u64 v[34:35], v[2:3], 0, s[16:17]
	global_store_dword v[34:35], v67, off
	s_or_b32 s8, s10, 28
	s_mov_b32 s9, s7
	s_lshl_b64 s[16:17], s[8:9], 16
	v_lshl_add_u64 v[34:35], v[2:3], 0, s[16:17]
	global_store_dword v[34:35], v68, off
	s_or_b32 s8, s10, 29
	s_mov_b32 s9, s7
	s_lshl_b64 s[16:17], s[8:9], 16
	v_lshl_add_u64 v[34:35], v[2:3], 0, s[16:17]
	global_store_dword v[34:35], v69, off
	s_or_b32 s8, s10, 30
	s_mov_b32 s9, s7
	s_lshl_b64 s[16:17], s[8:9], 16
	v_lshl_add_u64 v[34:35], v[2:3], 0, s[16:17]
	global_store_dword v[34:35], v70, off
	s_or_b32 s8, s10, 31
	s_mov_b32 s9, s7
	s_lshl_b64 s[16:17], s[8:9], 16
	v_lshl_add_u64 v[34:35], v[2:3], 0, s[16:17]
	global_store_dword v[34:35], v71, off
	s_mov_b32 s6, s2
	s_lshl_b64 s[6:7], s[6:7], 16
	s_waitcnt vmcnt(0)
	s_barrier
	s_and_saveexec_b64 s[8:9], s[14:15]
	s_cbranch_execz .LBB0_1375
	s_add_i32 s10, 0, 0x22160
	v_mov_b32_e32 v2, s10
	s_waitcnt vmcnt(0) expcnt(0) lgkmcnt(0)
	ds_read_b32 v4, v2
	s_add_i32 s10, 0, 0x22164
	v_mov_b32_e32 v2, s10
	ds_read_b32 v2, v2
	s_waitcnt lgkmcnt(1)
	v_cmp_ne_u32_e32 vcc, 0, v4
	s_cbranch_vccnz .LBB0_1339
	v_readlane_b32 s16, v251, 53
	v_readlane_b32 s17, v251, 54
	s_load_dwordx2 s[10:11], s[16:17], 0x4
	s_mov_b32 s33, 1
	v_mov_b32_e32 v18, 0
	s_waitcnt lgkmcnt(0)
	s_mul_i32 s10, s10, s11
	s_lshl_b32 s76, s10, 8
	s_add_u32 s10, s34, 0x4200
	s_addc_u32 s11, s35, 0
	s_add_u32 s16, s34, 0x4400
	s_addc_u32 s17, s35, 0
	s_add_u32 s18, s34, 0x4500
	s_addc_u32 s19, s35, 0
	s_add_u32 s20, s34, 0x4600
	s_addc_u32 s21, s35, 0
	s_add_u32 s22, s34, 0x4700
	s_addc_u32 s23, s35, 0
	s_add_u32 s24, s34, 0x4800
	s_addc_u32 s25, s35, 0
	s_add_u32 s26, s34, 0x4900
	s_addc_u32 s27, s35, 0
	s_add_u32 s28, s34, 0x4a00
	s_addc_u32 s29, s35, 0
	s_add_u32 s30, s34, 0x4b00
	s_addc_u32 s31, s35, 0
	s_add_u32 s38, s34, 0x4c00
	s_addc_u32 s39, s35, 0
	s_add_u32 s40, s34, 0x4d00
	s_addc_u32 s41, s35, 0
	s_add_u32 s42, s34, 0x4e00
	s_addc_u32 s43, s35, 0
	s_add_u32 s46, s34, 0x4f00
	s_addc_u32 s47, s35, 0
	s_add_u32 s48, s34, 0x5000
	s_addc_u32 s49, s35, 0
	s_add_u32 s50, s34, 0x5100
	s_addc_u32 s51, s35, 0
	s_add_u32 s54, s34, 0x5200
	s_addc_u32 s55, s35, 0
	s_add_u32 s68, s34, 0x5300
	s_addc_u32 s69, s35, 0
	s_branch .LBB0_1327
